# recurrence fix-up phase: the up-to-7 trailing single-chunk carry steps now load all their carries at once (one memory latency instead of seven), on top of the pipelined 8-chunk loop
# baseline (speedup 1.0000x reference)
;   DI bf16_t* h() const { return (bf16_t*)(ws + OFF_H); }
; DI void phase_scan_fix(const Params& p) {
;     ...
;     for (; cc < c; ++cc) h = *(const f32x4*)(cA + (size_t)cc * 1024) * h + *(const f32x4*)(cH + (size_t)cc * 1024);
.LBB0_685:
	s_mov_b32 s98, 0x200000
	s_mov_b32 s99, 0
	v_lshl_add_u64 v[158:159], v[8:9], 0, s[98:99]
	global_load_dwordx4 v[100:103], v[8:9], off
	global_load_dwordx4 v[104:107], v[158:159], off
	v_lshl_add_u64 v[8:9], v[8:9], 0, s[26:27]
	v_lshl_add_u64 v[158:159], v[158:159], 0, s[26:27]
	global_load_dwordx4 v[108:111], v[8:9], off
	global_load_dwordx4 v[112:115], v[158:159], off
	v_lshl_add_u64 v[8:9], v[8:9], 0, s[26:27]
	v_lshl_add_u64 v[158:159], v[158:159], 0, s[26:27]
	global_load_dwordx4 v[116:119], v[8:9], off
	global_load_dwordx4 v[120:123], v[158:159], off
	v_lshl_add_u64 v[8:9], v[8:9], 0, s[26:27]
	v_lshl_add_u64 v[158:159], v[158:159], 0, s[26:27]
	global_load_dwordx4 v[124:127], v[8:9], off
	global_load_dwordx4 v[128:131], v[158:159], off
	v_lshl_add_u64 v[8:9], v[8:9], 0, s[26:27]
	v_lshl_add_u64 v[158:159], v[158:159], 0, s[26:27]
	global_load_dwordx4 v[132:135], v[8:9], off
	global_load_dwordx4 v[136:139], v[158:159], off
	v_lshl_add_u64 v[8:9], v[8:9], 0, s[26:27]
	v_lshl_add_u64 v[158:159], v[158:159], 0, s[26:27]
	global_load_dwordx4 v[140:143], v[8:9], off
	global_load_dwordx4 v[144:147], v[158:159], off
	v_lshl_add_u64 v[8:9], v[8:9], 0, s[26:27]
	v_lshl_add_u64 v[158:159], v[158:159], 0, s[26:27]
	global_load_dwordx4 v[148:151], v[8:9], off
	global_load_dwordx4 v[152:155], v[158:159], off
	s_waitcnt vmcnt(12)
	v_pk_fma_f32 v[4:5], v[4:5], v[102:103], v[106:107]
	v_pk_fma_f32 v[2:3], v[2:3], v[100:101], v[104:105]
	v_add_u32_e32 v12, 1, v12
	v_cmp_lt_u32_e32 vcc, v12, v14
	s_and_b64 exec, exec, vcc
	s_cbranch_execz .LBB0_687
	s_waitcnt vmcnt(10)
	v_pk_fma_f32 v[4:5], v[4:5], v[110:111], v[114:115]
	v_pk_fma_f32 v[2:3], v[2:3], v[108:109], v[112:113]
	v_add_u32_e32 v12, 1, v12
	v_cmp_lt_u32_e32 vcc, v12, v14
	s_and_b64 exec, exec, vcc
	s_cbranch_execz .LBB0_687
	s_waitcnt vmcnt(8)
	v_pk_fma_f32 v[4:5], v[4:5], v[118:119], v[122:123]
	v_pk_fma_f32 v[2:3], v[2:3], v[116:117], v[120:121]
	v_add_u32_e32 v12, 1, v12
	v_cmp_lt_u32_e32 vcc, v12, v14
	s_and_b64 exec, exec, vcc
	s_cbranch_execz .LBB0_687
	s_waitcnt vmcnt(6)
	v_pk_fma_f32 v[4:5], v[4:5], v[126:127], v[130:131]
	v_pk_fma_f32 v[2:3], v[2:3], v[124:125], v[128:129]
	v_add_u32_e32 v12, 1, v12
	v_cmp_lt_u32_e32 vcc, v12, v14
	s_and_b64 exec, exec, vcc
	s_cbranch_execz .LBB0_687
	s_waitcnt vmcnt(4)
	v_pk_fma_f32 v[4:5], v[4:5], v[134:135], v[138:139]
	v_pk_fma_f32 v[2:3], v[2:3], v[132:133], v[136:137]
	v_add_u32_e32 v12, 1, v12
	v_cmp_lt_u32_e32 vcc, v12, v14
	s_and_b64 exec, exec, vcc
	s_cbranch_execz .LBB0_687
	s_waitcnt vmcnt(2)
	v_pk_fma_f32 v[4:5], v[4:5], v[142:143], v[146:147]
	v_pk_fma_f32 v[2:3], v[2:3], v[140:141], v[144:145]
	v_add_u32_e32 v12, 1, v12
	v_cmp_lt_u32_e32 vcc, v12, v14
	s_and_b64 exec, exec, vcc
	s_cbranch_execz .LBB0_687
	s_waitcnt vmcnt(0)
	v_pk_fma_f32 v[4:5], v[4:5], v[150:151], v[154:155]
	v_pk_fma_f32 v[2:3], v[2:3], v[148:149], v[152:153]
